# fold per-MFMA lgkmcnt waits of each PV chunk / QK pair into one wait (diff and GQA loops)
# speedup vs baseline: 1.0231x; 1.0012x over previous
; #define MFMA(a, b, c) __builtin_amdgcn_mfma_f32_32x32x16_bf16((a), (b), (c), 0, 0, 0)
; DI float fexp2(float x) { return __builtin_amdgcn_exp2f(x); }
; DI void flash_pass_q2(f32x16 (&o)[2][2], const u16* __restrict__ Qp0, const u16* __restrict__ Qp1,
;                       const u16* __restrict__ Kb, int ldk, const u16* __restrict__ Vt, int S, int ntiles, char* lds) {
;     ...
;     {
;       bf16x8 ka[4], kb_[4];
; #pragma unroll
;       for (int ks = 0; ks < 4; ++ks) {
;         const int co = ((2 * ks + h) ^ ksw) << 4;
;         ka[ks] = *(const bf16x8*)(st + pr * 128 + co);
;         kb_[ks] = *(const bf16x8*)(st + (32 + pr) * 128 + co);
;       }
;       asm volatile("" ::: "memory");
; #pragma unroll
;       for (int ks = 0; ks < 4; ++ks) {
;         s[0][0] = MFMA(ka[ks], q[0][ks], s[0][0]);
;         s[0][1] = MFMA(kb_[ks], q[0][ks], s[0][1]);
;         s[1][0] = MFMA(ka[ks], q[1][ks], s[1][0]);
;         s[1][1] = MFMA(kb_[ks], q[1][ks], s[1][1]);
;       }
;     }
;     bf16x8 pf[2][2][2];
; #pragma unroll
;     for (int hq = 0; hq < 2; ++hq) {
;       float t[32];
; #pragma unroll
;       for (int i = 0; i < 16; ++i) { t[i] = s[hq][0][i]; t[16 + i] = s[hq][1][i]; }
;       float mx = t[0];
; #pragma unroll
;       for (int e = 1; e < 32; ++e) mx = fmaxf(mx, t[e]);
;       mx = fmaxf(mx, __shfl_xor(mx, 32));
;       if (__builtin_amdgcn_ballot_w64(mx > m_run[hq] + 8.f) != 0ull) {
;         const float m_new = fmaxf(m_run[hq], mx);
;         const float alpha = fexp2(m_run[hq] - m_new);
;         l_run[hq] *= alpha;
;         m_run[hq] = m_new;
; #pragma unroll
;         for (int mv = 0; mv < 2; ++mv)
; #pragma unroll
;           for (int i = 0; i < 16; ++i) o[hq][mv][i] *= alpha;
;       }
;       float ls = 0.f;
; #pragma unroll
;       for (int e = 0; e < 32; ++e) { t[e] = fexp2(t[e] - m_run[hq]); ls += t[e]; }
;       l_run[hq] += ls;
.Lg2_noloadf:
	s_or_b64 exec, exec, s[20:21]
	v_cmp_eq_u32_e32 vcc, s22, v185
	s_waitcnt lgkmcnt(4)
	v_mfma_f32_32x32x16_bf16 v[128:143], v[2:5], v[168:171], 0
	v_mfma_f32_32x32x16_bf16 v[112:127], v[6:9], v[168:171], 0
	v_mfma_f32_32x32x16_bf16 v[96:111], v[2:5], v[172:175], 0
	v_mfma_f32_32x32x16_bf16 v[80:95], v[6:9], v[172:175], 0
	s_or_b64 s[18:19], vcc, s[18:19]
	v_add_u32_e32 v249, v11, v235
	ds_read_b128 v[2:5], v249
	ds_read_b128 v[6:9], v249 offset:4096
	s_waitcnt lgkmcnt(4)
	v_mfma_f32_32x32x16_bf16 v[128:143], v[12:15], v[164:167], v[128:143]
	v_mfma_f32_32x32x16_bf16 v[112:127], v[240:243], v[164:167], v[112:127]
	v_mfma_f32_32x32x16_bf16 v[96:111], v[12:15], v[160:163], v[96:111]
	v_mfma_f32_32x32x16_bf16 v[80:95], v[240:243], v[160:163], v[80:95]
	v_add_u32_e32 v249, v11, v234
	ds_read_b128 v[12:15], v249
	ds_read_b128 v[240:243], v249 offset:4096
	s_waitcnt lgkmcnt(2)
	v_mfma_f32_32x32x16_bf16 v[128:143], v[2:5], v[156:159], v[128:143]
	v_mfma_f32_32x32x16_bf16 v[112:127], v[6:9], v[156:159], v[112:127]
	v_mfma_f32_32x32x16_bf16 v[96:111], v[2:5], v[152:155], v[96:111]
	v_mfma_f32_32x32x16_bf16 v[80:95], v[6:9], v[152:155], v[80:95]
	v_add_u32_e32 v249, v248, v232
	ds_read_b128 v[2:5], v249 offset:8192
	ds_read_b128 v[6:9], v249 offset:12288
	s_waitcnt lgkmcnt(2)
	v_mfma_f32_32x32x16_bf16 v[128:143], v[12:15], v[148:151], v[128:143]
	v_mfma_f32_32x32x16_bf16 v[112:127], v[240:243], v[148:151], v[112:127]
	v_mfma_f32_32x32x16_bf16 v[96:111], v[12:15], v[144:147], v[96:111]
	v_mfma_f32_32x32x16_bf16 v[80:95], v[240:243], v[144:147], v[80:95]
	v_add_u32_e32 v249, v248, v231
	ds_read_b128 v[12:15], v249 offset:8192
	ds_read_b128 v[240:243], v249 offset:12288
	s_nop 5
	v_exp_f32_e32 v128, v128
	v_exp_f32_e32 v129, v129
	v_exp_f32_e32 v130, v130
	v_exp_f32_e32 v131, v131
	v_exp_f32_e32 v132, v132
	v_exp_f32_e32 v133, v133
	v_exp_f32_e32 v134, v134
	v_exp_f32_e32 v135, v135
	v_exp_f32_e32 v136, v136
	v_exp_f32_e32 v137, v137
	v_add_f32_e32 v210, v128, v130
	v_add_f32_e32 v246, v129, v131
	v_exp_f32_e32 v138, v138
	v_exp_f32_e32 v139, v139
	v_add_f32_e32 v210, v210, v132
	v_add_f32_e32 v246, v246, v133
	v_exp_f32_e32 v140, v140
	v_exp_f32_e32 v141, v141
	v_add_f32_e32 v210, v210, v134
	v_add_f32_e32 v246, v246, v135
	v_exp_f32_e32 v142, v142
	v_exp_f32_e32 v143, v143
	v_add_f32_e32 v210, v210, v136
	v_add_f32_e32 v246, v246, v137
	v_exp_f32_e32 v112, v112
	v_exp_f32_e32 v113, v113
	v_add_f32_e32 v210, v210, v138
	v_add_f32_e32 v246, v246, v139
	v_exp_f32_e32 v114, v114
	v_exp_f32_e32 v115, v115
	v_add_f32_e32 v210, v210, v140
	v_add_f32_e32 v246, v246, v141
	v_exp_f32_e32 v116, v116
	v_exp_f32_e32 v117, v117
	v_add_f32_e32 v210, v210, v142
	v_add_f32_e32 v246, v246, v143
	v_exp_f32_e32 v118, v118
	v_exp_f32_e32 v119, v119
	v_add_f32_e32 v210, v210, v112
	v_add_f32_e32 v246, v246, v113
	v_exp_f32_e32 v120, v120
	v_exp_f32_e32 v121, v121
	v_add_f32_e32 v210, v210, v114
	v_add_f32_e32 v246, v246, v115
	v_exp_f32_e32 v122, v122
	v_exp_f32_e32 v123, v123
	v_add_f32_e32 v210, v210, v116
	v_add_f32_e32 v246, v246, v117
	v_exp_f32_e32 v124, v124
	v_exp_f32_e32 v125, v125
	v_add_f32_e32 v210, v210, v118
	v_add_f32_e32 v246, v246, v119
	v_exp_f32_e32 v126, v126
	v_exp_f32_e32 v127, v127
	v_add_f32_e32 v210, v210, v120
	v_add_f32_e32 v246, v246, v121
	v_add_f32_e32 v210, v210, v122
	v_add_f32_e32 v246, v246, v123
	v_add_f32_e32 v210, v210, v124
	v_add_f32_e32 v246, v246, v125
	v_add_f32_e32 v210, v210, v126
	v_add_f32_e32 v246, v246, v127
	v_add_f32_e32 v210, v210, v246
	v_cmp_lt_f32_e32 vcc, 0x5d800000, v210
	s_cbranch_vccnz .Lg3_ovf0
	v_cmp_gt_f32_e32 vcc, s100, v210
	s_cbranch_vccnz .Lg3_unf0
; #define MFMA(a, b, c) __builtin_amdgcn_mfma_f32_32x32x16_bf16((a), (b), (c), 0, 0, 0)
; DI float fexp2(float x) { return __builtin_amdgcn_exp2f(x); }
; DI void flash_pass_q2(f32x16 (&o)[2][2], const u16* __restrict__ Qp0, const u16* __restrict__ Qp1,
;                       const u16* __restrict__ Kb, int ldk, const u16* __restrict__ Vt, int S, int ntiles, char* lds) {
;     ...
;       float ls = 0.f;
; #pragma unroll
;       for (int e = 0; e < 32; ++e) { t[e] = fexp2(t[e] - m_run[hq]); ls += t[e]; }
;       l_run[hq] += ls;
; #pragma unroll
;       for (int kb = 0; kb < 2; ++kb)
; #pragma unroll
;         for (int c2 = 0; c2 < 2; ++c2) {
;           const int e0 = kb * 16 + c2 * 8;
;           u32x4 pw = {pk_bf16(t[e0], t[e0 + 1]), pk_bf16(t[e0 + 2], t[e0 + 3]), pk_bf16(t[e0 + 4], t[e0 + 5]), pk_bf16(t[e0 + 6], t[e0 + 7])};
;           pf[hq][kb][c2] = __builtin_bit_cast(bf16x8, pw);
;         }
;     }
;     bf16x8 vf[2][2][2];
; #pragma unroll
;     for (int kb = 0; kb < 2; ++kb)
; #pragma unroll
;       for (int c2 = 0; c2 < 2; ++c2) {
;         const int co = ((4 * kb + 2 * c2 + h) ^ vsw) << 4;
; #pragma unroll
;         for (int mv = 0; mv < 2; ++mv) vf[kb][c2][mv] = *(const bf16x8*)(st + 8192 + (mv * 32 + r) * 128 + co);
;       }
;     asm volatile("" ::: "memory");
; #pragma unroll
;     for (int kb = 0; kb < 2; ++kb)
; #pragma unroll
;       for (int c2 = 0; c2 < 2; ++c2)
; #pragma unroll
;         for (int mv = 0; mv < 2; ++mv) {
;           o[0][mv] = MFMA(vf[kb][c2][mv], pf[0][kb][c2], o[0][mv]);
;           o[1][mv] = MFMA(vf[kb][c2][mv], pf[1][kb][c2], o[1][mv]);
;         }
;     __syncthreads();
	v_add_f32_e32 v0, v0, v210
	v_cvt_pk_bf16_f32 v128, v128, v129
	v_cvt_pk_bf16_f32 v129, v130, v131
	v_cvt_pk_bf16_f32 v130, v132, v133
	v_cvt_pk_bf16_f32 v131, v134, v135
	v_cvt_pk_bf16_f32 v136, v136, v137
	v_cvt_pk_bf16_f32 v137, v138, v139
	v_cvt_pk_bf16_f32 v138, v140, v141
	v_cvt_pk_bf16_f32 v139, v142, v143
	v_cvt_pk_bf16_f32 v112, v112, v113
	v_cvt_pk_bf16_f32 v113, v114, v115
	v_cvt_pk_bf16_f32 v114, v116, v117
	v_cvt_pk_bf16_f32 v115, v118, v119
	v_cvt_pk_bf16_f32 v120, v120, v121
	v_cvt_pk_bf16_f32 v121, v122, v123
	v_cvt_pk_bf16_f32 v122, v124, v125
	v_cvt_pk_bf16_f32 v123, v126, v127
	s_waitcnt lgkmcnt(0)
	v_mfma_f32_32x32x16_bf16 v[64:79], v[2:5], v[128:131], v[64:79]
	v_mfma_f32_32x32x16_bf16 v[48:63], v[6:9], v[128:131], v[48:63]
	v_mfma_f32_32x32x16_bf16 v[64:79], v[12:15], v[136:139], v[64:79]
	v_mfma_f32_32x32x16_bf16 v[48:63], v[240:243], v[136:139], v[48:63]
	v_exp_f32_e32 v96, v96
	v_exp_f32_e32 v97, v97
	v_exp_f32_e32 v98, v98
	v_exp_f32_e32 v99, v99
	v_exp_f32_e32 v100, v100
	v_exp_f32_e32 v101, v101
	v_exp_f32_e32 v102, v102
	v_exp_f32_e32 v103, v103
	v_exp_f32_e32 v104, v104
	v_exp_f32_e32 v105, v105
	v_add_f32_e32 v210, v96, v98
	v_add_f32_e32 v246, v97, v99
	v_exp_f32_e32 v106, v106
	v_exp_f32_e32 v107, v107
	v_add_f32_e32 v210, v210, v100
	v_add_f32_e32 v246, v246, v101
	v_exp_f32_e32 v108, v108
	v_exp_f32_e32 v109, v109
	v_add_f32_e32 v210, v210, v102
	v_add_f32_e32 v246, v246, v103
	v_exp_f32_e32 v110, v110
	v_exp_f32_e32 v111, v111
	v_add_f32_e32 v210, v210, v104
	v_add_f32_e32 v246, v246, v105
	v_exp_f32_e32 v80, v80
	v_exp_f32_e32 v81, v81
	v_add_f32_e32 v210, v210, v106
	v_add_f32_e32 v246, v246, v107
	v_exp_f32_e32 v82, v82
	v_exp_f32_e32 v83, v83
	v_add_f32_e32 v210, v210, v108
	v_add_f32_e32 v246, v246, v109
	v_exp_f32_e32 v84, v84
	v_exp_f32_e32 v85, v85
	v_add_f32_e32 v210, v210, v110
	v_add_f32_e32 v246, v246, v111
	v_exp_f32_e32 v86, v86
	v_exp_f32_e32 v87, v87
	v_add_f32_e32 v210, v210, v80
	v_add_f32_e32 v246, v246, v81
	v_exp_f32_e32 v88, v88
	v_exp_f32_e32 v89, v89
	v_add_f32_e32 v210, v210, v82
	v_add_f32_e32 v246, v246, v83
	v_exp_f32_e32 v90, v90
	v_exp_f32_e32 v91, v91
	v_add_f32_e32 v210, v210, v84
	v_add_f32_e32 v246, v246, v85
	v_exp_f32_e32 v92, v92
	v_exp_f32_e32 v93, v93
	v_add_f32_e32 v210, v210, v86
	v_add_f32_e32 v246, v246, v87
	v_exp_f32_e32 v94, v94
	v_exp_f32_e32 v95, v95
	v_add_f32_e32 v210, v210, v88
	v_add_f32_e32 v246, v246, v89
	v_add_f32_e32 v210, v210, v90
	v_add_f32_e32 v246, v246, v91
	v_add_f32_e32 v210, v210, v92
	v_add_f32_e32 v246, v246, v93
	v_add_f32_e32 v210, v210, v94
	v_add_f32_e32 v246, v246, v95
	v_add_f32_e32 v210, v210, v246
	v_cmp_lt_f32_e32 vcc, 0x5d800000, v210
	s_cbranch_vccnz .Lg3_ovf1
	v_cmp_gt_f32_e32 vcc, s100, v210
	s_cbranch_vccnz .Lg3_unf1
	v_add_f32_e32 v229, v229, v210
	v_cvt_pk_bf16_f32 v96, v96, v97
	v_cvt_pk_bf16_f32 v97, v98, v99
	v_cvt_pk_bf16_f32 v98, v100, v101
	v_cvt_pk_bf16_f32 v99, v102, v103
	v_cvt_pk_bf16_f32 v104, v104, v105
	v_cvt_pk_bf16_f32 v105, v106, v107
	v_cvt_pk_bf16_f32 v106, v108, v109
	v_cvt_pk_bf16_f32 v107, v110, v111
	v_cvt_pk_bf16_f32 v80, v80, v81
	v_cvt_pk_bf16_f32 v81, v82, v83
	v_cvt_pk_bf16_f32 v82, v84, v85
	v_cvt_pk_bf16_f32 v83, v86, v87
	v_cvt_pk_bf16_f32 v88, v88, v89
	v_cvt_pk_bf16_f32 v89, v90, v91
	v_cvt_pk_bf16_f32 v90, v92, v93
	v_cvt_pk_bf16_f32 v91, v94, v95
	v_mfma_f32_32x32x16_bf16 v[32:47], v[2:5], v[96:99], v[32:47]
	v_mfma_f32_32x32x16_bf16 v[16:31], v[6:9], v[96:99], v[16:31]
	v_add_u32_e32 v249, v248, v230
	ds_read_b128 v[2:5], v249 offset:8192
	ds_read_b128 v[6:9], v249 offset:12288
	v_mfma_f32_32x32x16_bf16 v[32:47], v[12:15], v[104:107], v[32:47]
	v_mfma_f32_32x32x16_bf16 v[16:31], v[240:243], v[104:107], v[16:31]
	v_add_u32_e32 v249, v248, v228
	ds_read_b128 v[12:15], v249 offset:8192
	ds_read_b128 v[240:243], v249 offset:12288
	s_waitcnt lgkmcnt(2)
	v_mfma_f32_32x32x16_bf16 v[64:79], v[2:5], v[112:115], v[64:79]
	v_mfma_f32_32x32x16_bf16 v[48:63], v[6:9], v[112:115], v[48:63]
	v_mfma_f32_32x32x16_bf16 v[32:47], v[2:5], v[80:83], v[32:47]
	v_mfma_f32_32x32x16_bf16 v[16:31], v[6:9], v[80:83], v[16:31]
	s_waitcnt lgkmcnt(0)
	v_mfma_f32_32x32x16_bf16 v[64:79], v[12:15], v[120:123], v[64:79]
	v_mfma_f32_32x32x16_bf16 v[48:63], v[240:243], v[120:123], v[48:63]
	v_mfma_f32_32x32x16_bf16 v[32:47], v[12:15], v[88:91], v[32:47]
	v_mfma_f32_32x32x16_bf16 v[16:31], v[240:243], v[88:91], v[16:31]
	v_mov_b32_e32 v14, s23
	s_waitcnt lgkmcnt(0)
	s_barrier
	s_andn2_b64 exec, exec, s[18:19]
	s_mov_b32 s100, 0
	s_cbranch_execnz .LBB0_280
	s_branch .LBB0_286

; #define MFMA(a, b, c) __builtin_amdgcn_mfma_f32_32x32x16_bf16((a), (b), (c), 0, 0, 0)
; DI float fexp2(float x) { return __builtin_amdgcn_exp2f(x); }
; DI void flash_pass_q2(f32x16 (&o)[2][2], const u16* __restrict__ Qp0, const u16* __restrict__ Qp1,
;                       const u16* __restrict__ Kb, int ldk, const u16* __restrict__ Vt, int S, int ntiles, char* lds) {
;     ...
;     {
;       bf16x8 ka[4], kb_[4];
; #pragma unroll
;       for (int ks = 0; ks < 4; ++ks) {
;         const int co = ((2 * ks + h) ^ ksw) << 4;
;         ka[ks] = *(const bf16x8*)(st + pr * 128 + co);
;         kb_[ks] = *(const bf16x8*)(st + (32 + pr) * 128 + co);
;       }
;       asm volatile("" ::: "memory");
; #pragma unroll
;       for (int ks = 0; ks < 4; ++ks) {
;         s[0][0] = MFMA(ka[ks], q[0][ks], s[0][0]);
;         s[0][1] = MFMA(kb_[ks], q[0][ks], s[0][1]);
;         s[1][0] = MFMA(ka[ks], q[1][ks], s[1][0]);
;         s[1][1] = MFMA(kb_[ks], q[1][ks], s[1][1]);
;       }
;     }
;     bf16x8 pf[2][2][2];
; #pragma unroll
;     for (int hq = 0; hq < 2; ++hq) {
;       float t[32];
; #pragma unroll
;       for (int i = 0; i < 16; ++i) { t[i] = s[hq][0][i]; t[16 + i] = s[hq][1][i]; }
;       float mx = t[0];
; #pragma unroll
;       for (int e = 1; e < 32; ++e) mx = fmaxf(mx, t[e]);
;       mx = fmaxf(mx, __shfl_xor(mx, 32));
;       if (__builtin_amdgcn_ballot_w64(mx > m_run[hq] + 8.f) != 0ull) {
;         const float m_new = fmaxf(m_run[hq], mx);
;         const float alpha = fexp2(m_run[hq] - m_new);
;         l_run[hq] *= alpha;
;         m_run[hq] = m_new;
; #pragma unroll
;         for (int mv = 0; mv < 2; ++mv)
; #pragma unroll
;           for (int i = 0; i < 16; ++i) o[hq][mv][i] *= alpha;
;       }
;       float ls = 0.f;
; #pragma unroll
;       for (int e = 0; e < 32; ++e) { t[e] = fexp2(t[e] - m_run[hq]); ls += t[e]; }
;       l_run[hq] += ls;
; #pragma unroll
;       for (int kb = 0; kb < 2; ++kb)
; #pragma unroll
;         for (int c2 = 0; c2 < 2; ++c2) {
;           const int e0 = kb * 16 + c2 * 8;
;           u32x4 pw = {pk_bf16(t[e0], t[e0 + 1]), pk_bf16(t[e0 + 2], t[e0 + 3]), pk_bf16(t[e0 + 4], t[e0 + 5]), pk_bf16(t[e0 + 6], t[e0 + 7])};
;           pf[hq][kb][c2] = __builtin_bit_cast(bf16x8, pw);
;         }
.Lg2_noload:
	s_or_b64 exec, exec, s[20:21]
	v_cmp_eq_u32_e32 vcc, s22, v185
	s_waitcnt lgkmcnt(4)
	v_mfma_f32_32x32x16_bf16 v[128:143], v[2:5], v[168:171], 0
	v_mfma_f32_32x32x16_bf16 v[112:127], v[6:9], v[168:171], 0
	v_mfma_f32_32x32x16_bf16 v[96:111], v[2:5], v[172:175], 0
	v_mfma_f32_32x32x16_bf16 v[80:95], v[6:9], v[172:175], 0
	s_or_b64 s[18:19], vcc, s[18:19]
	v_add_u32_e32 v249, v11, v235
	ds_read_b128 v[2:5], v249
	ds_read_b128 v[6:9], v249 offset:4096
	s_waitcnt lgkmcnt(4)
	v_mfma_f32_32x32x16_bf16 v[128:143], v[12:15], v[164:167], v[128:143]
	v_mfma_f32_32x32x16_bf16 v[112:127], v[240:243], v[164:167], v[112:127]
	v_mfma_f32_32x32x16_bf16 v[96:111], v[12:15], v[160:163], v[96:111]
	v_mfma_f32_32x32x16_bf16 v[80:95], v[240:243], v[160:163], v[80:95]
	v_add_u32_e32 v249, v11, v234
	ds_read_b128 v[12:15], v249
	ds_read_b128 v[240:243], v249 offset:4096
	s_waitcnt lgkmcnt(2)
	v_mfma_f32_32x32x16_bf16 v[128:143], v[2:5], v[156:159], v[128:143]
	v_mfma_f32_32x32x16_bf16 v[112:127], v[6:9], v[156:159], v[112:127]
	v_mfma_f32_32x32x16_bf16 v[96:111], v[2:5], v[152:155], v[96:111]
	v_mfma_f32_32x32x16_bf16 v[80:95], v[6:9], v[152:155], v[80:95]
	v_add_u32_e32 v249, v248, v232
	ds_read_b128 v[2:5], v249 offset:8192
	ds_read_b128 v[6:9], v249 offset:12288
	s_waitcnt lgkmcnt(2)
	v_mfma_f32_32x32x16_bf16 v[128:143], v[12:15], v[148:151], v[128:143]
	v_mfma_f32_32x32x16_bf16 v[112:127], v[240:243], v[148:151], v[112:127]
	v_mfma_f32_32x32x16_bf16 v[96:111], v[12:15], v[144:147], v[96:111]
	v_mfma_f32_32x32x16_bf16 v[80:95], v[240:243], v[144:147], v[80:95]
	v_add_u32_e32 v249, v248, v231
	ds_read_b128 v[12:15], v249 offset:8192
	ds_read_b128 v[240:243], v249 offset:12288
.Lg2_sm0:
	s_nop 5
	v_sub_f32_e32 v128, v128, v10
	v_sub_f32_e32 v129, v129, v10
	v_sub_f32_e32 v130, v130, v10
	v_sub_f32_e32 v131, v131, v10
	v_sub_f32_e32 v132, v132, v10
	v_sub_f32_e32 v133, v133, v10
	v_sub_f32_e32 v134, v134, v10
	v_sub_f32_e32 v135, v135, v10
	v_sub_f32_e32 v136, v136, v10
	v_sub_f32_e32 v137, v137, v10
	v_sub_f32_e32 v138, v138, v10
	v_sub_f32_e32 v139, v139, v10
	v_sub_f32_e32 v140, v140, v10
	v_sub_f32_e32 v141, v141, v10
	v_sub_f32_e32 v142, v142, v10
	v_sub_f32_e32 v143, v143, v10
	v_sub_f32_e32 v112, v112, v10
	v_sub_f32_e32 v113, v113, v10
	v_sub_f32_e32 v114, v114, v10
	v_sub_f32_e32 v115, v115, v10
	v_sub_f32_e32 v116, v116, v10
	v_sub_f32_e32 v117, v117, v10
	v_sub_f32_e32 v118, v118, v10
	v_sub_f32_e32 v119, v119, v10
	v_sub_f32_e32 v120, v120, v10
	v_sub_f32_e32 v121, v121, v10
	v_sub_f32_e32 v122, v122, v10
	v_sub_f32_e32 v123, v123, v10
	v_sub_f32_e32 v124, v124, v10
	v_sub_f32_e32 v125, v125, v10
	v_sub_f32_e32 v126, v126, v10
	v_sub_f32_e32 v127, v127, v10
	v_exp_f32_e32 v128, v128
	v_exp_f32_e32 v129, v129
	v_exp_f32_e32 v130, v130
	v_exp_f32_e32 v131, v131
	v_exp_f32_e32 v132, v132
	v_exp_f32_e32 v133, v133
	v_exp_f32_e32 v134, v134
	v_exp_f32_e32 v135, v135
	v_exp_f32_e32 v136, v136
	v_exp_f32_e32 v137, v137
	v_add_f32_e32 v210, v128, v130
	v_add_f32_e32 v246, v129, v131
	v_exp_f32_e32 v138, v138
	v_exp_f32_e32 v139, v139
	v_add_f32_e32 v210, v210, v132
	v_add_f32_e32 v246, v246, v133
	v_exp_f32_e32 v140, v140
	v_exp_f32_e32 v141, v141
	v_add_f32_e32 v210, v210, v134
	v_add_f32_e32 v246, v246, v135
	v_exp_f32_e32 v142, v142
	v_exp_f32_e32 v143, v143
	v_add_f32_e32 v210, v210, v136
	v_add_f32_e32 v246, v246, v137
	v_exp_f32_e32 v112, v112
	v_exp_f32_e32 v113, v113
	v_add_f32_e32 v210, v210, v138
	v_add_f32_e32 v246, v246, v139
	v_exp_f32_e32 v114, v114
	v_exp_f32_e32 v115, v115
	v_add_f32_e32 v210, v210, v140
	v_add_f32_e32 v246, v246, v141
	v_exp_f32_e32 v116, v116
	v_exp_f32_e32 v117, v117
	v_add_f32_e32 v210, v210, v142
	v_add_f32_e32 v246, v246, v143
	v_exp_f32_e32 v118, v118
	v_exp_f32_e32 v119, v119
	v_add_f32_e32 v210, v210, v112
	v_add_f32_e32 v246, v246, v113
	v_exp_f32_e32 v120, v120
	v_exp_f32_e32 v121, v121
	v_add_f32_e32 v210, v210, v114
	v_add_f32_e32 v246, v246, v115
	v_exp_f32_e32 v122, v122
	v_exp_f32_e32 v123, v123
	v_add_f32_e32 v210, v210, v116
	v_add_f32_e32 v246, v246, v117
	v_exp_f32_e32 v124, v124
	v_exp_f32_e32 v125, v125
	v_add_f32_e32 v210, v210, v118
	v_add_f32_e32 v246, v246, v119
	v_exp_f32_e32 v126, v126
	v_exp_f32_e32 v127, v127
	v_add_f32_e32 v210, v210, v120
	v_add_f32_e32 v246, v246, v121
	v_add_f32_e32 v210, v210, v122
	v_add_f32_e32 v246, v246, v123
	v_add_f32_e32 v210, v210, v124
	v_add_f32_e32 v246, v246, v125
	v_add_f32_e32 v210, v210, v126
	v_add_f32_e32 v246, v246, v127
	v_add_f32_e32 v210, v210, v246
	v_cmp_lt_f32_e32 vcc, 0x5d800000, v210
	s_cbranch_vccnz .Lg2_fix0
	v_add_f32_e32 v0, v0, v210
	v_cvt_pk_bf16_f32 v128, v128, v129
	v_cvt_pk_bf16_f32 v129, v130, v131
	v_cvt_pk_bf16_f32 v130, v132, v133
	v_cvt_pk_bf16_f32 v131, v134, v135
	v_cvt_pk_bf16_f32 v136, v136, v137
	v_cvt_pk_bf16_f32 v137, v138, v139
	v_cvt_pk_bf16_f32 v138, v140, v141
	v_cvt_pk_bf16_f32 v139, v142, v143
	v_cvt_pk_bf16_f32 v112, v112, v113
	v_cvt_pk_bf16_f32 v113, v114, v115
	v_cvt_pk_bf16_f32 v114, v116, v117
	v_cvt_pk_bf16_f32 v115, v118, v119
	v_cvt_pk_bf16_f32 v120, v120, v121
	v_cvt_pk_bf16_f32 v121, v122, v123
	v_cvt_pk_bf16_f32 v122, v124, v125
	v_cvt_pk_bf16_f32 v123, v126, v127
	s_waitcnt lgkmcnt(0)
	v_mfma_f32_32x32x16_bf16 v[64:79], v[2:5], v[128:131], v[64:79]
	v_mfma_f32_32x32x16_bf16 v[48:63], v[6:9], v[128:131], v[48:63]
	v_mfma_f32_32x32x16_bf16 v[64:79], v[12:15], v[136:139], v[64:79]
	v_mfma_f32_32x32x16_bf16 v[48:63], v[240:243], v[136:139], v[48:63]
; #define MFMA(a, b, c) __builtin_amdgcn_mfma_f32_32x32x16_bf16((a), (b), (c), 0, 0, 0)
; DI float fexp2(float x) { return __builtin_amdgcn_exp2f(x); }
; DI void flash_pass_q2(f32x16 (&o)[2][2], const u16* __restrict__ Qp0, const u16* __restrict__ Qp1,
;                       const u16* __restrict__ Kb, int ldk, const u16* __restrict__ Vt, int S, int ntiles, char* lds) {
;     ...
;       float ls = 0.f;
; #pragma unroll
;       for (int e = 0; e < 32; ++e) { t[e] = fexp2(t[e] - m_run[hq]); ls += t[e]; }
;       l_run[hq] += ls;
; #pragma unroll
;       for (int kb = 0; kb < 2; ++kb)
; #pragma unroll
;         for (int c2 = 0; c2 < 2; ++c2) {
;           const int e0 = kb * 16 + c2 * 8;
;           u32x4 pw = {pk_bf16(t[e0], t[e0 + 1]), pk_bf16(t[e0 + 2], t[e0 + 3]), pk_bf16(t[e0 + 4], t[e0 + 5]), pk_bf16(t[e0 + 6], t[e0 + 7])};
;           pf[hq][kb][c2] = __builtin_bit_cast(bf16x8, pw);
;         }
;     }
;     bf16x8 vf[2][2][2];
; #pragma unroll
;     for (int kb = 0; kb < 2; ++kb)
; #pragma unroll
;       for (int c2 = 0; c2 < 2; ++c2) {
;         const int co = ((4 * kb + 2 * c2 + h) ^ vsw) << 4;
; #pragma unroll
;         for (int mv = 0; mv < 2; ++mv) vf[kb][c2][mv] = *(const bf16x8*)(st + 8192 + (mv * 32 + r) * 128 + co);
;       }
;     asm volatile("" ::: "memory");
; #pragma unroll
;     for (int kb = 0; kb < 2; ++kb)
; #pragma unroll
;       for (int c2 = 0; c2 < 2; ++c2)
; #pragma unroll
;         for (int mv = 0; mv < 2; ++mv) {
;           o[0][mv] = MFMA(vf[kb][c2][mv], pf[0][kb][c2], o[0][mv]);
;           o[1][mv] = MFMA(vf[kb][c2][mv], pf[1][kb][c2], o[1][mv]);
;         }
;     __syncthreads();
.Lg2_sm1:
	v_sub_f32_e32 v96, v96, v233
	v_sub_f32_e32 v97, v97, v233
	v_sub_f32_e32 v98, v98, v233
	v_sub_f32_e32 v99, v99, v233
	v_sub_f32_e32 v100, v100, v233
	v_sub_f32_e32 v101, v101, v233
	v_sub_f32_e32 v102, v102, v233
	v_sub_f32_e32 v103, v103, v233
	v_sub_f32_e32 v104, v104, v233
	v_sub_f32_e32 v105, v105, v233
	v_sub_f32_e32 v106, v106, v233
	v_sub_f32_e32 v107, v107, v233
	v_sub_f32_e32 v108, v108, v233
	v_sub_f32_e32 v109, v109, v233
	v_sub_f32_e32 v110, v110, v233
	v_sub_f32_e32 v111, v111, v233
	v_sub_f32_e32 v80, v80, v233
	v_sub_f32_e32 v81, v81, v233
	v_sub_f32_e32 v82, v82, v233
	v_sub_f32_e32 v83, v83, v233
	v_sub_f32_e32 v84, v84, v233
	v_sub_f32_e32 v85, v85, v233
	v_sub_f32_e32 v86, v86, v233
	v_sub_f32_e32 v87, v87, v233
	v_sub_f32_e32 v88, v88, v233
	v_sub_f32_e32 v89, v89, v233
	v_sub_f32_e32 v90, v90, v233
	v_sub_f32_e32 v91, v91, v233
	v_sub_f32_e32 v92, v92, v233
	v_sub_f32_e32 v93, v93, v233
	v_sub_f32_e32 v94, v94, v233
	v_sub_f32_e32 v95, v95, v233
	v_exp_f32_e32 v96, v96
	v_exp_f32_e32 v97, v97
	v_exp_f32_e32 v98, v98
	v_exp_f32_e32 v99, v99
	v_exp_f32_e32 v100, v100
	v_exp_f32_e32 v101, v101
	v_exp_f32_e32 v102, v102
	v_exp_f32_e32 v103, v103
	v_exp_f32_e32 v104, v104
	v_exp_f32_e32 v105, v105
	v_add_f32_e32 v210, v96, v98
	v_add_f32_e32 v246, v97, v99
	v_exp_f32_e32 v106, v106
	v_exp_f32_e32 v107, v107
	v_add_f32_e32 v210, v210, v100
	v_add_f32_e32 v246, v246, v101
	v_exp_f32_e32 v108, v108
	v_exp_f32_e32 v109, v109
	v_add_f32_e32 v210, v210, v102
	v_add_f32_e32 v246, v246, v103
	v_exp_f32_e32 v110, v110
	v_exp_f32_e32 v111, v111
	v_add_f32_e32 v210, v210, v104
	v_add_f32_e32 v246, v246, v105
	v_exp_f32_e32 v80, v80
	v_exp_f32_e32 v81, v81
	v_add_f32_e32 v210, v210, v106
	v_add_f32_e32 v246, v246, v107
	v_exp_f32_e32 v82, v82
	v_exp_f32_e32 v83, v83
	v_add_f32_e32 v210, v210, v108
	v_add_f32_e32 v246, v246, v109
	v_exp_f32_e32 v84, v84
	v_exp_f32_e32 v85, v85
	v_add_f32_e32 v210, v210, v110
	v_add_f32_e32 v246, v246, v111
	v_exp_f32_e32 v86, v86
	v_exp_f32_e32 v87, v87
	v_add_f32_e32 v210, v210, v80
	v_add_f32_e32 v246, v246, v81
	v_exp_f32_e32 v88, v88
	v_exp_f32_e32 v89, v89
	v_add_f32_e32 v210, v210, v82
	v_add_f32_e32 v246, v246, v83
	v_exp_f32_e32 v90, v90
	v_exp_f32_e32 v91, v91
	v_add_f32_e32 v210, v210, v84
	v_add_f32_e32 v246, v246, v85
	v_exp_f32_e32 v92, v92
	v_exp_f32_e32 v93, v93
	v_add_f32_e32 v210, v210, v86
	v_add_f32_e32 v246, v246, v87
	v_exp_f32_e32 v94, v94
	v_exp_f32_e32 v95, v95
	v_add_f32_e32 v210, v210, v88
	v_add_f32_e32 v246, v246, v89
	v_add_f32_e32 v210, v210, v90
	v_add_f32_e32 v246, v246, v91
	v_add_f32_e32 v210, v210, v92
	v_add_f32_e32 v246, v246, v93
	v_add_f32_e32 v210, v210, v94
	v_add_f32_e32 v246, v246, v95
	v_add_f32_e32 v210, v210, v246
	v_cmp_lt_f32_e32 vcc, 0x5d800000, v210
	s_cbranch_vccnz .Lg2_fix1
	v_add_f32_e32 v229, v229, v210
	v_cvt_pk_bf16_f32 v96, v96, v97
	v_cvt_pk_bf16_f32 v97, v98, v99
	v_cvt_pk_bf16_f32 v98, v100, v101
	v_cvt_pk_bf16_f32 v99, v102, v103
	v_cvt_pk_bf16_f32 v104, v104, v105
	v_cvt_pk_bf16_f32 v105, v106, v107
	v_cvt_pk_bf16_f32 v106, v108, v109
	v_cvt_pk_bf16_f32 v107, v110, v111
	v_cvt_pk_bf16_f32 v80, v80, v81
	v_cvt_pk_bf16_f32 v81, v82, v83
	v_cvt_pk_bf16_f32 v82, v84, v85
	v_cvt_pk_bf16_f32 v83, v86, v87
	v_cvt_pk_bf16_f32 v88, v88, v89
	v_cvt_pk_bf16_f32 v89, v90, v91
	v_cvt_pk_bf16_f32 v90, v92, v93
	v_cvt_pk_bf16_f32 v91, v94, v95
	v_mfma_f32_32x32x16_bf16 v[32:47], v[2:5], v[96:99], v[32:47]
	v_mfma_f32_32x32x16_bf16 v[16:31], v[6:9], v[96:99], v[16:31]
	v_add_u32_e32 v249, v248, v230
	ds_read_b128 v[2:5], v249 offset:8192
	ds_read_b128 v[6:9], v249 offset:12288
	v_mfma_f32_32x32x16_bf16 v[32:47], v[12:15], v[104:107], v[32:47]
	v_mfma_f32_32x32x16_bf16 v[16:31], v[240:243], v[104:107], v[16:31]
	v_add_u32_e32 v249, v248, v228
	ds_read_b128 v[12:15], v249 offset:8192
	ds_read_b128 v[240:243], v249 offset:12288
	s_waitcnt lgkmcnt(2)
	v_mfma_f32_32x32x16_bf16 v[64:79], v[2:5], v[112:115], v[64:79]
	v_mfma_f32_32x32x16_bf16 v[48:63], v[6:9], v[112:115], v[48:63]
	v_mfma_f32_32x32x16_bf16 v[32:47], v[2:5], v[80:83], v[32:47]
	v_mfma_f32_32x32x16_bf16 v[16:31], v[6:9], v[80:83], v[16:31]
	s_waitcnt lgkmcnt(0)
	v_mfma_f32_32x32x16_bf16 v[64:79], v[12:15], v[120:123], v[64:79]
	v_mfma_f32_32x32x16_bf16 v[48:63], v[240:243], v[120:123], v[48:63]
	v_mfma_f32_32x32x16_bf16 v[32:47], v[12:15], v[88:91], v[32:47]
	v_mfma_f32_32x32x16_bf16 v[16:31], v[240:243], v[88:91], v[16:31]
	v_mov_b32_e32 v14, s23
	s_waitcnt lgkmcnt(0)
	s_barrier
	s_andn2_b64 exec, exec, s[18:19]
	s_cbranch_execnz .Lg3_slow
	s_branch .LBB0_286

; #define MFMA(a, b, c) __builtin_amdgcn_mfma_f32_32x32x16_bf16((a), (b), (c), 0, 0, 0)
; DI float fexp2(float x) { return __builtin_amdgcn_exp2f(x); }
; template <int DV, bool NA> ...
;     ...
;       {
;         bf16x8 ka[4], kb_[4];
; #pragma unroll
;         for (int ks = 0; ks < 4; ++ks) {
;           const int co = ((2 * ks + h) ^ ksw) << 4;
;           ka[ks] = *(const bf16x8*)(st + pr * 128 + co);
;           kb_[ks] = *(const bf16x8*)(st + (32 + pr) * 128 + co);
;         }
;         asm volatile("" ::: "memory");
; #pragma unroll
;         for (int ks = 0; ks < 4; ++ks) {
;           s0 = MFMA(ka[ks], q[ks], s0);
;           s1 = MFMA(kb_[ks], q[ks], s1);
;         }
;       }
;       bf16x8 vf0[2][DV / 32];
; #pragma unroll
;       for (int c2 = 0; c2 < 2; ++c2) {
;         const int co = ((2 * c2 + h) ^ vsw) << 4;
; #pragma unroll
;         for (int mv = 0; mv < DV / 32; ++mv) vf0[c2][mv] = *(const bf16x8*)(st + 8192 + (mv * 32 + r) * 128 + co);
;     ...
;       float ls = 0.f;
; #pragma unroll
;       for (int e = 0; e < 32; ++e) { t[e] = fexp2(t[e] - m_run); ls += t[e]; }
;       l_run += ls;
;       bf16x8 pf[2][2];
; #pragma unroll
;       for (int kb = 0; kb < 2; ++kb)
; #pragma unroll
;         for (int c2 = 0; c2 < 2; ++c2) {
;           const int e0 = kb * 16 + c2 * 8;
;           u32x4 pw = {pk_bf16(t[e0], t[e0 + 1]), pk_bf16(t[e0 + 2], t[e0 + 3]), pk_bf16(t[e0 + 4], t[e0 + 5]), pk_bf16(t[e0 + 6], t[e0 + 7])};
;           pf[kb][c2] = __builtin_bit_cast(bf16x8, pw);
;         }
;       bf16x8 vf1[2][DV / 32];
; #pragma unroll
;       for (int c2 = 0; c2 < 2; ++c2) {
;         const int co = ((4 + 2 * c2 + h) ^ vsw) << 4;
; #pragma unroll
;         for (int mv = 0; mv < DV / 32; ++mv) vf1[c2][mv] = *(const bf16x8*)(st + 8192 + (mv * 32 + r) * 128 + co);
;       }
;       asm volatile("" ::: "memory");
; #pragma unroll
;       for (int c2 = 0; c2 < 2; ++c2)
; #pragma unroll
;         for (int mv = 0; mv < DV / 32; ++mv) o[mv] = MFMA(vf0[c2][mv], pf[0][c2], o[mv]);
; #pragma unroll
;       for (int c2 = 0; c2 < 2; ++c2)
; #pragma unroll
;         for (int mv = 0; mv < DV / 32; ++mv) o[mv] = MFMA(vf1[c2][mv], pf[1][c2], o[mv]);
;     }
;     __syncthreads();
.Ldf_skipw_top:
	s_bitcmp1_b32 s31, 0
	s_cselect_b32 s22, 0x6000, 0
	v_add_u32_e32 v158, s22, v228
	v_add_u32_e32 v159, v158, v229
	ds_read_b128 v[0:3], v159
	ds_read_b128 v[4:7], v159 offset:4096
	v_add_u32_e32 v159, v158, v202
	ds_read_b128 v[8:11], v159
	ds_read_b128 v[12:15], v159 offset:4096
	v_add3_u32 v210, s22, v195, v178
	s_waitcnt lgkmcnt(2)
	v_mfma_f32_32x32x16_bf16 v[96:111], v[0:3], v[124:127], v[234:249]
	v_mfma_f32_32x32x16_bf16 v[80:95], v[4:7], v[124:127], v[234:249]
	v_add_u32_e32 v159, v158, v201
	ds_read_b128 v[0:3], v159
	ds_read_b128 v[4:7], v159 offset:4096
	s_waitcnt lgkmcnt(2)
	v_mfma_f32_32x32x16_bf16 v[96:111], v[8:11], v[120:123], v[96:111]
	v_mfma_f32_32x32x16_bf16 v[80:95], v[12:15], v[120:123], v[80:95]
	v_add_u32_e32 v159, v158, v200
	ds_read_b128 v[8:11], v159
	ds_read_b128 v[12:15], v159 offset:4096
	ds_read_b128 v[140:143], v210 offset:8192
	ds_read_b128 v[144:147], v210 offset:12288
	ds_read_b128 v[148:151], v210 offset:16384
	ds_read_b128 v[152:155], v210 offset:20480
	v_add3_u32 v230, s22, v183, v178
	s_waitcnt lgkmcnt(6)
	v_mfma_f32_32x32x16_bf16 v[96:111], v[0:3], v[116:119], v[96:111]
	v_mfma_f32_32x32x16_bf16 v[80:95], v[4:7], v[116:119], v[80:95]
	s_waitcnt lgkmcnt(4)
	v_mfma_f32_32x32x16_bf16 v[96:111], v[8:11], v[112:115], v[96:111]
	v_mfma_f32_32x32x16_bf16 v[80:95], v[12:15], v[112:115], v[80:95]
	ds_read_b128 v[0:3], v230 offset:8192
	ds_read_b128 v[4:7], v230 offset:12288
	ds_read_b128 v[8:11], v230 offset:16384
	ds_read_b128 v[12:15], v230 offset:20480
	v_cmp_eq_u32_e32 vcc, s29, v177
	v_add3_u32 v210, s22, v181, v178
	v_add3_u32 v230, s22, v179, v178
	s_or_b64 s[20:21], vcc, s[20:21]
.Ldf_exps:
	s_nop 2
	v_exp_f32_e32 v96, v96
	v_exp_f32_e32 v97, v97
	v_exp_f32_e32 v98, v98
	v_exp_f32_e32 v99, v99
	v_exp_f32_e32 v100, v100
	v_exp_f32_e32 v101, v101
	v_exp_f32_e32 v102, v102
	v_exp_f32_e32 v103, v103
	v_exp_f32_e32 v104, v104
	v_exp_f32_e32 v105, v105
	v_add_f32_e32 v156, v96, v98
	v_add_f32_e32 v157, v97, v99
	v_exp_f32_e32 v106, v106
	v_exp_f32_e32 v107, v107
	v_add_f32_e32 v156, v156, v100
	v_add_f32_e32 v157, v157, v101
	v_exp_f32_e32 v108, v108
	v_exp_f32_e32 v109, v109
	v_add_f32_e32 v156, v156, v102
	v_add_f32_e32 v157, v157, v103
	v_exp_f32_e32 v110, v110
	v_exp_f32_e32 v111, v111
	v_add_f32_e32 v156, v156, v104
	v_add_f32_e32 v157, v157, v105
	v_exp_f32_e32 v80, v80
	v_exp_f32_e32 v81, v81
	v_add_f32_e32 v156, v156, v106
	v_add_f32_e32 v157, v157, v107
	v_exp_f32_e32 v82, v82
	v_exp_f32_e32 v83, v83
	v_add_f32_e32 v156, v156, v108
	v_add_f32_e32 v157, v157, v109
	v_exp_f32_e32 v84, v84
	v_exp_f32_e32 v85, v85
	v_add_f32_e32 v156, v156, v110
	v_add_f32_e32 v157, v157, v111
	v_exp_f32_e32 v86, v86
	v_exp_f32_e32 v87, v87
	v_add_f32_e32 v156, v156, v80
	v_add_f32_e32 v157, v157, v81
	v_exp_f32_e32 v88, v88
	v_exp_f32_e32 v89, v89
	v_add_f32_e32 v156, v156, v82
	v_add_f32_e32 v157, v157, v83
	v_exp_f32_e32 v90, v90
	v_exp_f32_e32 v91, v91
	v_add_f32_e32 v156, v156, v84
	v_add_f32_e32 v157, v157, v85
	v_exp_f32_e32 v92, v92
	v_exp_f32_e32 v93, v93
	v_add_f32_e32 v156, v156, v86
	v_add_f32_e32 v157, v157, v87
	v_exp_f32_e32 v94, v94
	v_exp_f32_e32 v95, v95
	v_add_f32_e32 v156, v156, v88
	v_add_f32_e32 v157, v157, v89
	v_add_f32_e32 v156, v156, v90
	v_add_f32_e32 v157, v157, v91
	v_add_f32_e32 v156, v156, v92
	v_add_f32_e32 v157, v157, v93
	v_add_f32_e32 v156, v156, v94
	v_add_f32_e32 v157, v157, v95
	v_add_f32_e32 v156, v156, v157
	v_cmp_lt_f32_e32 vcc, s100, v156
	s_cbranch_vccnz .Ldf_fix
	v_add_f32_e32 v180, v180, v156
	v_cvt_pk_bf16_f32 v96, v96, v97
	v_cvt_pk_bf16_f32 v97, v98, v99
	v_cvt_pk_bf16_f32 v98, v100, v101
	v_cvt_pk_bf16_f32 v99, v102, v103
	s_waitcnt lgkmcnt(4)
	s_nop 0
	v_mfma_f32_32x32x16_bf16 v[64:79], v[140:143], v[96:99], v[64:79]
	v_cvt_pk_bf16_f32 v104, v104, v105
	v_mfma_f32_32x32x16_bf16 v[48:63], v[144:147], v[96:99], v[48:63]
	v_cvt_pk_bf16_f32 v105, v106, v107
	v_mfma_f32_32x32x16_bf16 v[32:47], v[148:151], v[96:99], v[32:47]
	v_cvt_pk_bf16_f32 v106, v108, v109
	v_mfma_f32_32x32x16_bf16 v[16:31], v[152:155], v[96:99], v[16:31]
	v_cvt_pk_bf16_f32 v107, v110, v111
	ds_read_b128 v[140:143], v210 offset:8192
	ds_read_b128 v[144:147], v210 offset:12288
	ds_read_b128 v[148:151], v210 offset:16384
	ds_read_b128 v[152:155], v210 offset:20480
	s_waitcnt lgkmcnt(4)
	v_mfma_f32_32x32x16_bf16 v[64:79], v[0:3], v[104:107], v[64:79]
	v_cvt_pk_bf16_f32 v80, v80, v81
	v_mfma_f32_32x32x16_bf16 v[48:63], v[4:7], v[104:107], v[48:63]
	v_cvt_pk_bf16_f32 v81, v82, v83
	v_mfma_f32_32x32x16_bf16 v[32:47], v[8:11], v[104:107], v[32:47]
	v_cvt_pk_bf16_f32 v82, v84, v85
	v_mfma_f32_32x32x16_bf16 v[16:31], v[12:15], v[104:107], v[16:31]
	v_cvt_pk_bf16_f32 v83, v86, v87
	ds_read_b128 v[0:3], v230 offset:8192
	ds_read_b128 v[4:7], v230 offset:12288
	ds_read_b128 v[8:11], v230 offset:16384
	ds_read_b128 v[12:15], v230 offset:20480
	s_waitcnt lgkmcnt(4)
	v_mfma_f32_32x32x16_bf16 v[64:79], v[140:143], v[80:83], v[64:79]
	v_cvt_pk_bf16_f32 v88, v88, v89
	v_mfma_f32_32x32x16_bf16 v[48:63], v[144:147], v[80:83], v[48:63]
	v_cvt_pk_bf16_f32 v89, v90, v91
	v_mfma_f32_32x32x16_bf16 v[32:47], v[148:151], v[80:83], v[32:47]
	v_cvt_pk_bf16_f32 v90, v92, v93
	v_mfma_f32_32x32x16_bf16 v[16:31], v[152:155], v[80:83], v[16:31]
	v_cvt_pk_bf16_f32 v91, v94, v95
	s_waitcnt lgkmcnt(0)
	s_nop 0
	v_mfma_f32_32x32x16_bf16 v[64:79], v[0:3], v[88:91], v[64:79]
	v_mfma_f32_32x32x16_bf16 v[48:63], v[4:7], v[88:91], v[48:63]
	v_mfma_f32_32x32x16_bf16 v[32:47], v[8:11], v[88:91], v[32:47]
	v_mfma_f32_32x32x16_bf16 v[16:31], v[12:15], v[88:91], v[16:31]
	s_cmp_eq_u32 s101, 1
	s_cbranch_scc1 .Ldf_skipw_bot
	s_add_i32 s22, s31, 2
	v_add_u32_e32 v159, s30, v203
	v_cmp_lt_u32_e32 vcc, s22, v185
	s_waitcnt vmcnt(1)
	ds_write_b128 v159, v[128:131]
	ds_write_b128 v159, v[132:135] offset:8192
	s_waitcnt vmcnt(0)
	ds_write_b128 v159, v[136:139] offset:16384
	s_and_saveexec_b64 s[22:23], vcc
	s_cbranch_execz .Ldf_noload_b
	global_load_dwordx4 v[128:131], v[174:175], off
	global_load_dwordx4 v[132:135], v[170:171], off
	global_load_dwordx4 v[136:139], v[172:173], off
	v_lshl_add_u64 v[170:171], v[170:171], 0, s[4:5]
	v_lshl_add_u64 v[172:173], v[172:173], 0, s[4:5]
	v_lshl_add_u64 v[174:175], v[174:175], 0, s[82:83]

; #define MFMA(a, b, c) __builtin_amdgcn_mfma_f32_32x32x16_bf16((a), (b), (c), 0, 0, 0)
; DI float fexp2(float x) { return __builtin_amdgcn_exp2f(x); }
; template <int DV, bool NA> ...
;     ...
;       {
;         bf16x8 ka[4], kb_[4];
; #pragma unroll
;         for (int ks = 0; ks < 4; ++ks) {
;           const int co = ((2 * ks + h) ^ ksw) << 4;
;           ka[ks] = *(const bf16x8*)(st + pr * 128 + co);
;           kb_[ks] = *(const bf16x8*)(st + (32 + pr) * 128 + co);
;         }
;         asm volatile("" ::: "memory");
; #pragma unroll
;         for (int ks = 0; ks < 4; ++ks) {
;           s0 = MFMA(ka[ks], q[ks], s0);
;           s1 = MFMA(kb_[ks], q[ks], s1);
;         }
;     ...
;       float mx = t[0];
; #pragma unroll
;       for (int e = 1; e < 32; ++e) mx = fmaxf(mx, t[e]);
;       mx = fmaxf(mx, __shfl_xor(mx, 32));
;       if (__builtin_amdgcn_ballot_w64(mx > m_run + 8.f) != 0ull) {
;         const float m_new = fmaxf(m_run, mx);
;         const float alpha = fexp2(m_run - m_new);
;         l_run *= alpha;
;         m_run = m_new;
; #pragma unroll
;         for (int mv = 0; mv < DV / 32; ++mv)
; #pragma unroll
;           for (int i = 0; i < 16; ++i) o[mv][i] *= alpha;
;       }
;       float ls = 0.f;
; #pragma unroll
;       for (int e = 0; e < 32; ++e) { t[e] = fexp2(t[e] - m_run); ls += t[e]; }
;       l_run += ls;
.Ldf_fix:
	s_waitcnt lgkmcnt(0)
	v_add_u32_e32 v158, s22, v228
	v_add_u32_e32 v159, v158, v229
	ds_read_b128 v[0:3], v159
	ds_read_b128 v[4:7], v159 offset:4096
	v_add_u32_e32 v159, v158, v202
	ds_read_b128 v[8:11], v159
	ds_read_b128 v[12:15], v159 offset:4096
	s_waitcnt lgkmcnt(2)
	v_mfma_f32_32x32x16_bf16 v[96:111], v[0:3], v[124:127], v[234:249]
	v_mfma_f32_32x32x16_bf16 v[80:95], v[4:7], v[124:127], v[234:249]
	v_add_u32_e32 v159, v158, v201
	ds_read_b128 v[0:3], v159
	ds_read_b128 v[4:7], v159 offset:4096
	s_waitcnt lgkmcnt(2)
	v_mfma_f32_32x32x16_bf16 v[96:111], v[8:11], v[120:123], v[96:111]
	v_mfma_f32_32x32x16_bf16 v[80:95], v[12:15], v[120:123], v[80:95]
	v_add_u32_e32 v159, v158, v200
	ds_read_b128 v[8:11], v159
	ds_read_b128 v[12:15], v159 offset:4096
	v_add3_u32 v230, s22, v183, v178
	s_waitcnt lgkmcnt(2)
	v_mfma_f32_32x32x16_bf16 v[96:111], v[0:3], v[116:119], v[96:111]
	v_mfma_f32_32x32x16_bf16 v[80:95], v[4:7], v[116:119], v[80:95]
	s_waitcnt lgkmcnt(0)
	v_mfma_f32_32x32x16_bf16 v[96:111], v[8:11], v[112:115], v[96:111]
	v_mfma_f32_32x32x16_bf16 v[80:95], v[12:15], v[112:115], v[80:95]
	ds_read_b128 v[0:3], v230 offset:8192
	ds_read_b128 v[4:7], v230 offset:12288
	ds_read_b128 v[8:11], v230 offset:16384
	ds_read_b128 v[12:15], v230 offset:20480
	s_nop 6
	v_max3_f32 v156, v96, v97, v98
	v_max3_f32 v157, v105, v106, v107
	v_max3_f32 v158, v80, v81, v82
	v_max3_f32 v159, v89, v90, v91
	v_max3_f32 v156, v156, v99, v100
	v_max3_f32 v157, v157, v108, v109
	v_max3_f32 v158, v158, v83, v84
	v_max3_f32 v159, v159, v92, v93
	v_max3_f32 v156, v156, v101, v102
	v_max3_f32 v157, v157, v110, v111
	v_max3_f32 v158, v158, v85, v86
	v_max3_f32 v159, v159, v94, v95
	v_max3_f32 v156, v156, v103, v104
	v_max3_f32 v158, v158, v87, v88
	v_max3_f32 v156, v156, v157, v158
	v_max_f32_e32 v156, v156, v159
	v_mov_b32_e32 v157, v156
	v_mov_b32_e32 v158, s100
	s_nop 0
	v_permlane32_swap_b32_e32 v156, v157
	v_max_f32_e32 v156, v156, v157
	v_max_f32_e32 v158, 0xff800000, v158
	v_cmp_class_f32_e64 vcc, v158, 4
	v_max_f32_e32 v157, 0, v156
	s_nop 1
	v_cndmask_b32_e32 v157, v157, v156, vcc
	s_mov_b32 s100, 0x5d800000
	v_add_f32_e32 v182, v182, v157
	v_min_f32_e64 v158, -v157, 0
	v_exp_f32_e32 v158, v158
	v_sub_f32_e32 v234, v234, v157
	v_sub_f32_e32 v235, v235, v157
	v_sub_f32_e32 v236, v236, v157
	v_sub_f32_e32 v237, v237, v157
	v_sub_f32_e32 v238, v238, v157
	v_sub_f32_e32 v239, v239, v157
	v_sub_f32_e32 v240, v240, v157
	v_sub_f32_e32 v241, v241, v157
	v_sub_f32_e32 v242, v242, v157
	v_sub_f32_e32 v243, v243, v157
	v_sub_f32_e32 v244, v244, v157
	v_sub_f32_e32 v245, v245, v157
	v_sub_f32_e32 v246, v246, v157
	v_sub_f32_e32 v247, v247, v157
	v_sub_f32_e32 v248, v248, v157
	v_sub_f32_e32 v249, v249, v157
	v_sub_f32_e32 v80, v80, v157
	v_sub_f32_e32 v81, v81, v157
	v_sub_f32_e32 v82, v82, v157
	v_sub_f32_e32 v83, v83, v157
	v_sub_f32_e32 v84, v84, v157
	v_sub_f32_e32 v85, v85, v157
	v_sub_f32_e32 v86, v86, v157
	v_sub_f32_e32 v87, v87, v157
	v_sub_f32_e32 v88, v88, v157
	v_sub_f32_e32 v89, v89, v157
	v_sub_f32_e32 v90, v90, v157
	v_sub_f32_e32 v91, v91, v157
	v_sub_f32_e32 v92, v92, v157
	v_sub_f32_e32 v93, v93, v157
	v_sub_f32_e32 v94, v94, v157
	v_sub_f32_e32 v95, v95, v157
	v_sub_f32_e32 v96, v96, v157
	v_sub_f32_e32 v97, v97, v157
	v_sub_f32_e32 v98, v98, v157
	v_sub_f32_e32 v99, v99, v157
	v_sub_f32_e32 v100, v100, v157
	v_sub_f32_e32 v101, v101, v157
	v_sub_f32_e32 v102, v102, v157
	v_sub_f32_e32 v103, v103, v157
	v_sub_f32_e32 v104, v104, v157
	v_sub_f32_e32 v105, v105, v157
	v_sub_f32_e32 v106, v106, v157
	v_sub_f32_e32 v107, v107, v157
	v_sub_f32_e32 v108, v108, v157
	v_sub_f32_e32 v109, v109, v157
	v_sub_f32_e32 v110, v110, v157
	v_sub_f32_e32 v111, v111, v157
	v_pk_mul_f32 v[16:17], v[16:17], v[158:159] op_sel_hi:[1,0]
	v_pk_mul_f32 v[18:19], v[18:19], v[158:159] op_sel_hi:[1,0]
	v_pk_mul_f32 v[20:21], v[20:21], v[158:159] op_sel_hi:[1,0]
	v_pk_mul_f32 v[22:23], v[22:23], v[158:159] op_sel_hi:[1,0]
	v_pk_mul_f32 v[24:25], v[24:25], v[158:159] op_sel_hi:[1,0]
	v_pk_mul_f32 v[26:27], v[26:27], v[158:159] op_sel_hi:[1,0]
	v_pk_mul_f32 v[28:29], v[28:29], v[158:159] op_sel_hi:[1,0]
	v_pk_mul_f32 v[30:31], v[30:31], v[158:159] op_sel_hi:[1,0]
	v_pk_mul_f32 v[32:33], v[32:33], v[158:159] op_sel_hi:[1,0]
	v_pk_mul_f32 v[34:35], v[34:35], v[158:159] op_sel_hi:[1,0]
	v_pk_mul_f32 v[36:37], v[36:37], v[158:159] op_sel_hi:[1,0]
	v_pk_mul_f32 v[38:39], v[38:39], v[158:159] op_sel_hi:[1,0]
	v_pk_mul_f32 v[40:41], v[40:41], v[158:159] op_sel_hi:[1,0]
	v_pk_mul_f32 v[42:43], v[42:43], v[158:159] op_sel_hi:[1,0]
	v_pk_mul_f32 v[44:45], v[44:45], v[158:159] op_sel_hi:[1,0]
	v_pk_mul_f32 v[46:47], v[46:47], v[158:159] op_sel_hi:[1,0]
	v_pk_mul_f32 v[48:49], v[48:49], v[158:159] op_sel_hi:[1,0]
	v_pk_mul_f32 v[50:51], v[50:51], v[158:159] op_sel_hi:[1,0]
	v_pk_mul_f32 v[52:53], v[52:53], v[158:159] op_sel_hi:[1,0]
	v_pk_mul_f32 v[54:55], v[54:55], v[158:159] op_sel_hi:[1,0]
	v_pk_mul_f32 v[56:57], v[56:57], v[158:159] op_sel_hi:[1,0]
	v_pk_mul_f32 v[58:59], v[58:59], v[158:159] op_sel_hi:[1,0]
	v_pk_mul_f32 v[60:61], v[60:61], v[158:159] op_sel_hi:[1,0]
	v_pk_mul_f32 v[62:63], v[62:63], v[158:159] op_sel_hi:[1,0]
	v_pk_mul_f32 v[64:65], v[64:65], v[158:159] op_sel_hi:[1,0]
	v_pk_mul_f32 v[66:67], v[66:67], v[158:159] op_sel_hi:[1,0]
	v_pk_mul_f32 v[68:69], v[68:69], v[158:159] op_sel_hi:[1,0]
	v_pk_mul_f32 v[70:71], v[70:71], v[158:159] op_sel_hi:[1,0]
	v_pk_mul_f32 v[72:73], v[72:73], v[158:159] op_sel_hi:[1,0]
	v_pk_mul_f32 v[74:75], v[74:75], v[158:159] op_sel_hi:[1,0]
	v_pk_mul_f32 v[76:77], v[76:77], v[158:159] op_sel_hi:[1,0]
	v_pk_mul_f32 v[78:79], v[78:79], v[158:159] op_sel_hi:[1,0]
	v_mul_f32_e32 v180, v180, v158
	v_add3_u32 v230, s22, v179, v178
	s_branch .Ldf_exps
